# P4 wave-0 gate scans via DPP row_shr/row_bcast instead of 12 serial ds_bpermute round trips; U pass: first dot4c of each chain replaced by v_dot4_i32_i8 with zero addend (drops 28 zero-init moves per
# speedup vs baseline: 1.0095x; 1.0095x over previous
.LBB0_571:
	v_cndmask_b32_e64 v31, v31, 0, s[98:99]
	v_cndmask_b32_e64 v30, v30, 0, s[98:99]
	v_cndmask_b32_e64 v29, v29, 0, s[98:99]
	v_cndmask_b32_e64 v28, v28, 0, s[98:99]
	v_cndmask_b32_e64 v35, v35, 0, s[98:99]
	v_cndmask_b32_e64 v34, v34, 0, s[98:99]
	v_cndmask_b32_e64 v33, v33, 0, s[98:99]
	v_cndmask_b32_e64 v32, v32, 0, s[98:99]
	v_cndmask_b32_e64 v39, v39, 0, s[98:99]
	v_cndmask_b32_e64 v38, v38, 0, s[98:99]
	v_cndmask_b32_e64 v37, v37, 0, s[98:99]
	v_cndmask_b32_e64 v36, v36, 0, s[98:99]
	v_cndmask_b32_e64 v43, v43, 0, s[98:99]
	v_cndmask_b32_e64 v42, v42, 0, s[98:99]
	v_cndmask_b32_e64 v41, v41, 0, s[98:99]
	v_cndmask_b32_e64 v40, v40, 0, s[98:99]
	v_cndmask_b32_e64 v75, v215, 0, s[98:99]
	v_cndmask_b32_e64 v79, v214, 0, s[98:99]
	s_and_saveexec_b64 s[0:1], s[2:3]
	s_cbranch_execz .LBB0_573
	s_waitcnt vmcnt(0)
	ds_write_b32 v116, v89
	ds_write_b32 v117, v89
	v_max_f32_e32 v48, v79, v79
	v_mov_b32_e32 v44, v73
	s_nop 4
	s_nop 1
	v_add_f32_dpp v44, v44, v44 row_shr:1 row_mask:0xf bank_mask:0xf
	s_nop 1
	v_add_f32_dpp v44, v44, v44 row_shr:2 row_mask:0xf bank_mask:0xf
	s_nop 1
	v_add_f32_dpp v44, v44, v44 row_shr:4 row_mask:0xf bank_mask:0xf
	s_nop 1
	v_add_f32_dpp v44, v44, v44 row_shr:8 row_mask:0xf bank_mask:0xf
	s_nop 1
	v_add_f32_dpp v44, v44, v44 row_bcast:15 row_mask:0xa bank_mask:0xf
	s_nop 1
	v_add_f32_dpp v44, v44, v44 row_bcast:31 row_mask:0xc bank_mask:0xf
	v_sub_f32_e32 v45, v85, v44
	v_mov_b32_e32 v46, v45
	s_nop 1
	v_max_f32_dpp v46, v46, v46 row_shr:1 row_mask:0xf bank_mask:0xf
	s_nop 1
	v_max_f32_dpp v46, v46, v46 row_shr:2 row_mask:0xf bank_mask:0xf
	s_nop 1
	v_max_f32_dpp v46, v46, v46 row_shr:4 row_mask:0xf bank_mask:0xf
	s_nop 1
	v_max_f32_dpp v46, v46, v46 row_shr:8 row_mask:0xf bank_mask:0xf
	s_nop 1
	v_max_f32_dpp v46, v46, v46 row_bcast:15 row_mask:0xa bank_mask:0xf
	s_nop 1
	v_max_f32_dpp v46, v46, v46 row_bcast:31 row_mask:0xc bank_mask:0xf
	v_max_f32_e32 v46, v46, v46
	v_max_f32_e32 v46, v48, v46
	v_sub_f32_e32 v47, v79, v46
	v_add_f32_e32 v44, v44, v46
	v_mul_f32_e32 v47, 0x3fb8aa3b, v47
	v_mul_f32_e32 v44, 0xbfb8aa3b, v44
	v_exp_f32_e32 v47, v47
	v_exp_f32_e32 v44, v44
	ds_write_b32 v112, v45
	ds_write_b32 v113, v46
	ds_write_b32 v114, v47
	ds_write_b32 v115, v44
	ds_write_b32 v118, v89

.Lux_skip1:
	v_dot4c_i32_i8_e32 v138, v0, v64
	v_dot4c_i32_i8_e32 v178, v4, v64
	v_dot4c_i32_i8_e32 v185, v32, v64
	v_dot4c_i32_i8_e32 v186, v36, v64
	v_dot4c_i32_i8_e32 v138, v1, v65
	v_lshl_or_b32 v69, v69, 7, v137
	v_lshl_or_b32 v68, v68, 7, v174
	global_load_dwordx4 v[132:135], v68, s[14:15]
	global_load_dwordx4 v[128:131], v69, s[14:15]
	v_dot4c_i32_i8_e32 v178, v5, v65
	v_dot4c_i32_i8_e32 v185, v33, v65
	v_dot4c_i32_i8_e32 v186, v37, v65
	v_dot4c_i32_i8_e32 v138, v2, v66
	v_dot4c_i32_i8_e32 v178, v6, v66
	v_dot4c_i32_i8_e32 v185, v34, v66
	v_dot4c_i32_i8_e32 v186, v38, v66
	v_dot4c_i32_i8_e32 v138, v3, v67
	v_dot4c_i32_i8_e32 v178, v7, v67
	v_dot4c_i32_i8_e32 v185, v35, v67
	v_dot4c_i32_i8_e32 v186, v39, v67
	v_lshl_or_b32 v69, v70, 7, v174
	v_lshl_or_b32 v68, v71, 7, v137
	global_load_dwordx4 v[124:127], v69, s[14:15]
	global_load_dwordx4 v[120:123], v68, s[14:15]
	v_cndmask_b32_e64 v215, v185, v138, s[2:3]
	v_cndmask_b32_e64 v138, v138, v185, s[2:3]
	v_cndmask_b32_e64 v185, v178, v186, s[2:3]
	ds_bpermute_b32 v185, v201, v185
	v_dot4_i32_i8 v180, v12, v64, 0
	v_dot4_i32_i8 v210, v44, v64, 0
	v_dot4c_i32_i8_e32 v180, v13, v65
	v_dot4_i32_i8 v181, v16, v64, 0
	v_lshl_or_b32 v69, v72, 7, v174
	v_lshl_or_b32 v68, v73, 7, v137
	global_load_dwordx4 v[116:119], v69, s[14:15]
	global_load_dwordx4 v[112:115], v68, s[14:15]
	v_dot4c_i32_i8_e32 v210, v45, v65
	v_dot4_i32_i8 v211, v48, v64, 0
	v_dot4c_i32_i8_e32 v180, v14, v66
	v_dot4c_i32_i8_e32 v181, v17, v65
	v_dot4c_i32_i8_e32 v210, v46, v66
	v_dot4c_i32_i8_e32 v211, v49, v65
	v_dot4c_i32_i8_e32 v180, v15, v67
	v_dot4c_i32_i8_e32 v181, v18, v66
	v_dot4c_i32_i8_e32 v210, v47, v67
	v_dot4c_i32_i8_e32 v211, v50, v66
	v_cndmask_b32_e64 v178, v186, v178, s[2:3]
	v_lshl_or_b32 v69, v74, 7, v174
	v_lshl_or_b32 v68, v75, 7, v137
	global_load_dwordx4 v[108:111], v69, s[14:15]
	global_load_dwordx4 v[104:107], v68, s[14:15]
	v_dot4c_i32_i8_e32 v181, v19, v67
	v_dot4c_i32_i8_e32 v211, v51, v67
	s_waitcnt lgkmcnt(0)
	v_add_u32_e32 v178, v185, v178
	v_cndmask_b32_e64 v185, v210, v180, s[2:3]
	v_cndmask_b32_e64 v180, v180, v210, s[2:3]
	v_dot4_i32_i8 v179, v8, v64, 0
	v_dot4_i32_i8 v182, v20, v64, 0
	v_lshl_or_b32 v69, v76, 7, v174
	v_lshl_or_b32 v68, v77, 7, v137
	global_load_dwordx4 v[100:103], v69, s[14:15]
	global_load_dwordx4 v[96:99], v68, s[14:15]
	v_dot4_i32_i8 v187, v40, v64, 0
	v_dot4_i32_i8 v212, v52, v64, 0
	ds_bpermute_b32 v180, v201, v180
	v_cndmask_b32_e64 v186, v181, v211, s[2:3]
	v_dot4c_i32_i8_e32 v179, v9, v65
	v_dot4c_i32_i8_e32 v182, v21, v65
	v_dot4_i32_i8 v183, v24, v64, 0
	v_dot4c_i32_i8_e32 v187, v41, v65
	v_lshl_or_b32 v69, v78, 7, v174
	v_lshl_or_b32 v68, v79, 7, v137
	global_load_dwordx4 v[92:95], v69, s[14:15]
	global_load_dwordx4 v[88:91], v68, s[14:15]
	v_dot4c_i32_i8_e32 v212, v53, v65
	v_dot4_i32_i8 v213, v56, v64, 0
	ds_bpermute_b32 v186, v201, v186
	v_dot4c_i32_i8_e32 v179, v10, v66
	v_dot4c_i32_i8_e32 v182, v22, v66
	v_dot4c_i32_i8_e32 v183, v25, v65
	v_dot4_i32_i8 v184, v28, v64, 0
	v_dot4c_i32_i8_e32 v187, v42, v66
	v_dot4c_i32_i8_e32 v212, v54, v66
	v_dot4c_i32_i8_e32 v213, v57, v65
	v_lshl_or_b32 v68, v81, 7, v137
	v_lshl_or_b32 v69, v80, 7, v174
	global_load_dwordx4 v[84:87], v69, s[14:15]
	global_load_dwordx4 v[76:79], v68, s[14:15]
	v_dot4_i32_i8 v214, v60, v64, 0
	v_dot4c_i32_i8_e32 v179, v11, v67
	v_dot4c_i32_i8_e32 v182, v23, v67
	v_dot4c_i32_i8_e32 v183, v26, v66
	v_dot4c_i32_i8_e32 v184, v29, v65
	v_dot4c_i32_i8_e32 v187, v43, v67
	v_dot4c_i32_i8_e32 v212, v55, v67
	v_dot4c_i32_i8_e32 v213, v58, v66
	v_dot4c_i32_i8_e32 v214, v61, v65
	v_dot4c_i32_i8_e32 v183, v27, v67
	v_dot4c_i32_i8_e32 v184, v30, v66
	v_dot4c_i32_i8_e32 v213, v59, v67
	v_lshl_or_b32 v68, v83, 7, v137
	v_lshl_or_b32 v69, v82, 7, v174
	global_load_dwordx4 v[72:75], v69, s[14:15]
	global_load_dwordx4 v[68:71], v68, s[14:15]
	v_add_u32_e32 v231, s99, v230
	ds_read_b128 v[80:83], v231
	v_dot4c_i32_i8_e32 v214, v62, v66
	v_cndmask_b32_e64 v216, v179, v187, s[2:3]
	v_cndmask_b32_e64 v179, v187, v179, s[2:3]
	v_cndmask_b32_e64 v187, v182, v212, s[2:3]
	v_dot4c_i32_i8_e32 v184, v31, v67
	v_dot4c_i32_i8_e32 v214, v63, v67
	ds_bpermute_b32 v138, v201, v138
	ds_bpermute_b32 v187, v201, v187
	s_waitcnt lgkmcnt(3)
	v_add_u32_e32 v180, v180, v185
	v_cndmask_b32_e64 v181, v211, v181, s[2:3]
	v_cndmask_b32_e64 v185, v213, v183, s[2:3]
	v_cndmask_b32_e64 v183, v183, v213, s[2:3]
	ds_bpermute_b32 v216, v201, v216
	s_waitcnt lgkmcnt(3)
	v_add_u32_e32 v181, v186, v181
	ds_bpermute_b32 v183, v201, v183
	v_cndmask_b32_e64 v186, v184, v214, s[2:3]
	ds_bpermute_b32 v186, v201, v186
	v_cndmask_b32_e64 v182, v212, v182, s[2:3]
	s_waitcnt lgkmcnt(4)
	v_add_u32_e32 v138, v138, v215
	s_waitcnt lgkmcnt(3)
	v_add_u32_e32 v182, v187, v182
	s_waitcnt lgkmcnt(2)
	v_add_u32_e32 v179, v216, v179
	v_cndmask_b32_e64 v187, v138, v181, s[4:5]
	s_waitcnt lgkmcnt(1)
	v_add_u32_e32 v183, v183, v185
	v_cndmask_b32_e64 v184, v214, v184, s[2:3]
	v_cndmask_b32_e64 v138, v181, v138, s[4:5]
	v_cndmask_b32_e64 v181, v182, v178, s[4:5]
	v_cndmask_b32_e64 v178, v178, v182, s[4:5]
	s_waitcnt lgkmcnt(0)
	v_add_u32_e32 v184, v186, v184
	ds_bpermute_b32 v178, v202, v178
	v_cndmask_b32_e64 v182, v179, v183, s[4:5]
	ds_bpermute_b32 v187, v202, v187
	ds_bpermute_b32 v182, v202, v182
	v_cndmask_b32_e64 v185, v180, v184, s[4:5]
	ds_bpermute_b32 v185, v202, v185
	s_waitcnt lgkmcnt(3)
	v_add_u32_e32 v181, v178, v181
	v_cndmask_b32_e64 v178, v183, v179, s[4:5]
	s_waitcnt lgkmcnt(2)
	v_add_u32_e32 v138, v187, v138
	s_waitcnt lgkmcnt(1)
	v_add_u32_e32 v178, v182, v178
	v_cndmask_b32_e64 v179, v184, v180, s[4:5]
	s_waitcnt lgkmcnt(0)
	v_add_u32_e32 v179, v185, v179
	v_cndmask_b32_e64 v180, v138, v178, s[6:7]
	ds_bpermute_b32 v180, v203, v180
	v_cndmask_b32_e64 v182, v181, v179, s[6:7]
	ds_bpermute_b32 v182, v203, v182
	s_add_i32 s1, s61, 0xffffff00
	v_cndmask_b32_e64 v138, v178, v138, s[6:7]
	s_and_b32 s1, s1, 0x700
	s_waitcnt lgkmcnt(1)
	v_add_u32_e32 v178, v180, v138
	v_cndmask_b32_e64 v138, v179, v181, s[6:7]
	s_cmp_gt_u32 s0, 15
	s_waitcnt lgkmcnt(0)
	v_add_u32_e32 v179, v182, v138
	s_cselect_b64 s[14:15], -1, 0
	s_cmp_lt_u32 s0, 16
	v_lshl_add_u32 v138, s1, 2, v190
	s_cbranch_scc1 .LBB0_926
	ds_read_b64 v[180:181], v138
	s_waitcnt lgkmcnt(0)
	v_add_u32_e32 v178, v180, v178
	v_add_u32_e32 v179, v181, v179

.LBB0_928:
	s_waitcnt vmcnt(0)
	v_dot4_i32_i8 v138, v132, v80, 0
	global_load_dwordx4 v[0:3], v0, s[16:17]
	v_dot4_i32_i8 v132, v128, v80, 0
	v_dot4_i32_i8 v128, v124, v80, 0
	v_dot4_i32_i8 v124, v120, v80, 0
	global_load_dwordx4 v[4:7], v4, s[16:17]
	v_dot4_i32_i8 v120, v116, v80, 0
	v_dot4_i32_i8 v116, v112, v80, 0
	global_load_dwordx4 v[8:11], v8, s[16:17]
	v_dot4_i32_i8 v112, v108, v80, 0
	v_dot4_i32_i8 v108, v104, v80, 0
	v_dot4_i32_i8 v104, v100, v80, 0
	global_load_dwordx4 v[12:15], v12, s[16:17]
	v_dot4_i32_i8 v100, v96, v80, 0
	v_dot4_i32_i8 v96, v92, v80, 0
	v_dot4_i32_i8 v92, v88, v80, 0
	global_load_dwordx4 v[16:19], v16, s[16:17]
	v_dot4_i32_i8 v88, v84, v80, 0
	v_dot4c_i32_i8_e32 v138, v133, v81
	v_dot4c_i32_i8_e32 v104, v101, v81
	global_load_dwordx4 v[20:23], v20, s[16:17]
	v_dot4_i32_i8 v84, v76, v80, 0
	v_dot4c_i32_i8_e32 v138, v134, v82
	v_dot4c_i32_i8_e32 v132, v129, v81
	v_dot4c_i32_i8_e32 v104, v102, v82
	global_load_dwordx4 v[24:27], v24, s[16:17]
	v_dot4c_i32_i8_e32 v100, v97, v81
	v_dot4_i32_i8 v76, v72, v80, 0
	v_dot4c_i32_i8_e32 v138, v135, v83
	v_dot4c_i32_i8_e32 v132, v130, v82
	global_load_dwordx4 v[28:31], v28, s[16:17]
	v_dot4c_i32_i8_e32 v128, v125, v81
	v_dot4c_i32_i8_e32 v104, v103, v83
	v_dot4c_i32_i8_e32 v100, v98, v82
	v_dot4c_i32_i8_e32 v96, v93, v81
	v_dot4_i32_i8 v72, v68, v80, 0
	global_load_dwordx4 v[32:35], v32, s[16:17]
	v_dot4c_i32_i8_e32 v132, v131, v83
	v_dot4c_i32_i8_e32 v128, v126, v82
	v_dot4c_i32_i8_e32 v124, v121, v81
	v_dot4c_i32_i8_e32 v100, v99, v83
	v_dot4c_i32_i8_e32 v96, v94, v82
	global_load_dwordx4 v[36:39], v36, s[16:17]
	v_dot4c_i32_i8_e32 v92, v89, v81
	v_dot4c_i32_i8_e32 v72, v69, v81
	v_cndmask_b32_e64 v69, v138, v104, s[2:3]
	v_dot4c_i32_i8_e32 v128, v127, v83
	v_dot4c_i32_i8_e32 v124, v122, v82
	global_load_dwordx4 v[40:43], v40, s[16:17]
	v_dot4c_i32_i8_e32 v120, v117, v81
	v_dot4c_i32_i8_e32 v96, v95, v83
	v_dot4c_i32_i8_e32 v92, v90, v82
	v_dot4c_i32_i8_e32 v88, v85, v81
	v_dot4c_i32_i8_e32 v72, v70, v82
	global_load_dwordx4 v[44:47], v44, s[16:17]
	ds_bpermute_b32 v69, v201, v69
	v_cndmask_b32_e64 v70, v132, v100, s[2:3]
	v_dot4c_i32_i8_e32 v124, v123, v83
	v_dot4c_i32_i8_e32 v120, v118, v82
	v_dot4c_i32_i8_e32 v116, v113, v81
	global_load_dwordx4 v[48:51], v48, s[16:17]
	v_dot4c_i32_i8_e32 v92, v91, v83
	v_dot4c_i32_i8_e32 v88, v86, v82
	v_dot4c_i32_i8_e32 v84, v77, v81
	v_dot4c_i32_i8_e32 v72, v71, v83
	ds_bpermute_b32 v70, v201, v70
	v_cndmask_b32_e64 v71, v128, v96, s[2:3]
	global_load_dwordx4 v[52:55], v52, s[16:17]
	v_dot4c_i32_i8_e32 v120, v119, v83
	v_dot4c_i32_i8_e32 v116, v114, v82
	v_dot4c_i32_i8_e32 v88, v87, v83
	v_dot4c_i32_i8_e32 v84, v78, v82
	v_dot4c_i32_i8_e32 v76, v73, v81
	global_load_dwordx4 v[56:59], v56, s[16:17]
	ds_bpermute_b32 v71, v201, v71
	v_cndmask_b32_e64 v73, v124, v92, s[2:3]
	v_dot4c_i32_i8_e32 v116, v115, v83
	v_dot4c_i32_i8_e32 v84, v79, v83
	v_dot4c_i32_i8_e32 v76, v74, v82
	global_load_dwordx4 v[60:63], v60, s[16:17]
	ds_bpermute_b32 v73, v201, v73
	v_cndmask_b32_e64 v74, v120, v88, s[2:3]
	v_dot4c_i32_i8_e32 v76, v75, v83
	v_cndmask_b32_e64 v68, v104, v138, s[2:3]
	ds_bpermute_b32 v74, v201, v74
	v_cndmask_b32_e64 v75, v116, v84, s[2:3]
	s_waitcnt lgkmcnt(4)
	v_add_u32_e32 v68, v69, v68
	v_cndmask_b32_e64 v69, v100, v132, s[2:3]
	ds_bpermute_b32 v75, v201, v75
	s_waitcnt lgkmcnt(4)
	v_add_u32_e32 v69, v70, v69
	v_cndmask_b32_e64 v70, v96, v128, s[2:3]
	v_dot4c_i32_i8_e32 v112, v109, v81
	v_dot4c_i32_i8_e32 v108, v105, v81
	s_waitcnt lgkmcnt(3)
	v_add_u32_e32 v70, v71, v70
	v_cndmask_b32_e64 v71, v92, v124, s[2:3]
	v_dot4c_i32_i8_e32 v112, v110, v82
	v_dot4c_i32_i8_e32 v108, v106, v82
	s_waitcnt lgkmcnt(2)
	v_add_u32_e32 v71, v73, v71
	v_cndmask_b32_e64 v73, v88, v120, s[2:3]
	v_dot4c_i32_i8_e32 v112, v111, v83
	v_dot4c_i32_i8_e32 v108, v107, v83
	s_waitcnt lgkmcnt(1)
	v_add_u32_e32 v73, v74, v73
	v_cndmask_b32_e64 v74, v84, v116, s[2:3]
	s_waitcnt lgkmcnt(0)
	v_add_u32_e32 v74, v75, v74
	v_cndmask_b32_e64 v75, v76, v112, s[2:3]
	v_cndmask_b32_e64 v76, v112, v76, s[2:3]
	v_cndmask_b32_e64 v77, v108, v72, s[2:3]
	ds_bpermute_b32 v76, v201, v76
	ds_bpermute_b32 v77, v201, v77
	v_cndmask_b32_e64 v72, v72, v108, s[2:3]
	v_cndmask_b32_e64 v78, v68, v73, s[4:5]
	v_cndmask_b32_e64 v68, v73, v68, s[4:5]
	s_waitcnt lgkmcnt(1)
	v_add_u32_e32 v75, v76, v75
	s_waitcnt lgkmcnt(0)
	v_add_u32_e32 v72, v77, v72
	v_cndmask_b32_e64 v73, v74, v69, s[4:5]
	v_cndmask_b32_e64 v69, v69, v74, s[4:5]
	v_cndmask_b32_e64 v74, v70, v75, s[4:5]
	v_cndmask_b32_e64 v76, v71, v72, s[4:5]
	ds_bpermute_b32 v78, v202, v78
	ds_bpermute_b32 v69, v202, v69
	ds_bpermute_b32 v74, v202, v74
	ds_bpermute_b32 v76, v202, v76
	v_cndmask_b32_e64 v70, v75, v70, s[4:5]
	v_cndmask_b32_e64 v71, v72, v71, s[4:5]
	s_waitcnt lgkmcnt(3)
	v_add_u32_e32 v68, v78, v68
	s_waitcnt lgkmcnt(2)
	v_add_u32_e32 v69, v69, v73
	s_waitcnt lgkmcnt(1)
	v_add_u32_e32 v70, v74, v70
	s_waitcnt lgkmcnt(0)
	v_add_u32_e32 v71, v76, v71
	v_cndmask_b32_e64 v72, v68, v70, s[6:7]
	v_cndmask_b32_e64 v73, v69, v71, s[6:7]
	ds_bpermute_b32 v72, v203, v72
	ds_bpermute_b32 v73, v203, v73
	v_cndmask_b32_e64 v68, v70, v68, s[6:7]
	v_cndmask_b32_e64 v69, v71, v69, s[6:7]
	s_andn2_b64 vcc, exec, s[14:15]
	s_waitcnt lgkmcnt(1)
	v_add_u32_e32 v68, v72, v68
	s_waitcnt lgkmcnt(0)
	v_add_u32_e32 v69, v73, v69
	v_lshl_add_u32 v70, s65, 2, v190
	s_cbranch_vccnz .LBB0_923
	ds_read_b64 v[72:73], v70
	s_waitcnt lgkmcnt(0)
	v_add_u32_e32 v68, v72, v68
	v_add_u32_e32 v69, v73, v69
	s_branch .LBB0_923
